# prep small-weights section: the three gather loads per thread issued together before the stores (was load-wait-store x3)
# baseline (speedup 1.0000x reference)
; __device__ __forceinline__ bf16_t f2bf(float v) { return (bf16_t)(cvt_pk_bf16(v, 0.f) & 0xffffu); }
; __device__ __forceinline__ void prep_phase(const Params& p, LAS unsigned char* lds) {
;     ...
;     for (int e = gt; e < 2 * WSM_L; e += NGT) {
;         const int l = e / WSM_L, r = e % WSM_L; float v;
;         if (r < 256 * 512) { const int n = r >> 9, k = r & 255; const int g = n >> 6, d = n & 63, g2 = k >> 6, c = k & 63; v = (g == g2) ? p.w_fourier[(((size_t)l * 4 + g) * 64 + c) * 64 + d] : 0.f; }
;         else { const int r2 = r - 256 * 512, n = r2 >> 8, k = r2 & 255; v = p.w_conv_out[((size_t)l * 256 + k) * 256 + n]; }
;         ((bf16_t*)(ws + WS_WSM))[e] = f2bf(v);
.LBB0_81:
	v_readlane_b32 s0, v253, 1
	v_readlane_b32 s1, v253, 2
	s_or_b64 exec, exec, s[0:1]
	v_readlane_b32 s4, v252, 0
	v_readlane_b32 s10, v252, 6
	s_mov_b32 s1, 0x60000
	v_readlane_b32 s5, v252, 1
	s_lshl_b32 s0, s10, 9
	v_cmp_gt_i32_e32 vcc, s1, v68
	v_readlane_b32 s6, v252, 2
	v_readlane_b32 s7, v252, 3
	v_readlane_b32 s8, v252, 4
	v_readlane_b32 s9, v252, 5
	v_readlane_b32 s11, v252, 7
	s_and_saveexec_b64 s[4:5], vcc
	s_cbranch_execz .LBB0_90
	v_readlane_b32 s8, v252, 0
	v_readlane_b32 s12, v252, 4
	v_readlane_b32 s9, v252, 1
	v_readlane_b32 s13, v252, 5
	s_add_u32 s6, s12, 0x2f00000
	v_lshlrev_b32_e32 v1, 8, v66
	s_addc_u32 s7, s13, 0
	v_lshl_add_u32 v1, s2, 17, v1
	s_lshl_b32 s1, s0, 8
	s_mov_b64 s[8:9], 0
	s_mov_b32 s3, 0x2aaaaaab
	s_mov_b32 s12, 0x1ffff
	v_mov_b32_e32 v3, 0
	s_mov_b32 s13, 0x5ffff
	v_mov_b32_e32 v4, v68
	v_readlane_b32 s10, v252, 2
	v_readlane_b32 s11, v252, 3
	v_readlane_b32 s14, v252, 6
	v_readlane_b32 s15, v252, 7
	v_mov_b32_e32 v24, v4
	v_mul_hi_i32 v2, v4, s3
	v_lshrrev_b32_e32 v5, 31, v2
	v_ashrrev_i32_e32 v2, 15, v2
	v_add_u32_e32 v6, v2, v5
	v_mul_i32_i24_e32 v2, 0x30000, v6
	v_sub_u32_e32 v5, v4, v2
	v_cmp_lt_i32_e32 vcc, s12, v5
	s_and_saveexec_b64 s[10:11], vcc
	s_xor_b64 s[10:11], exec, s[10:11]
	s_cbranch_execz .Lsw0_87
	v_lshlrev_b32_e32 v2, 8, v2
	v_ashrrev_i32_e32 v7, 31, v6
	v_sub_u32_e32 v2, v1, v2
	v_readlane_b32 s16, v252, 48
	v_and_b32_e32 v2, 0xff00, v2
	v_lshlrev_b64 v[6:7], 18, v[6:7]
	v_readlane_b32 s22, v252, 54
	v_readlane_b32 s23, v252, 55
	v_add_u32_e32 v5, 0xfffe0000, v5
	v_lshlrev_b32_e32 v2, 2, v2
	v_lshl_add_u64 v[6:7], s[22:23], 0, v[6:7]
	v_lshl_add_u64 v[6:7], v[6:7], 0, v[2:3]
	v_lshrrev_b32_e32 v2, 6, v5
	v_and_b32_e32 v2, 0x3fffffc, v2
	v_lshl_add_u64 v[6:7], v[6:7], 0, v[2:3]
	global_load_dword v20, v[6:7], off
	v_readlane_b32 s17, v252, 49
	v_readlane_b32 s18, v252, 50
	v_readlane_b32 s19, v252, 51
	v_readlane_b32 s20, v252, 52
	v_readlane_b32 s21, v252, 53
	v_readlane_b32 s24, v252, 56
	v_readlane_b32 s25, v252, 57
	v_readlane_b32 s26, v252, 58
	v_readlane_b32 s27, v252, 59
	v_readlane_b32 s28, v252, 60
	v_readlane_b32 s29, v252, 61
	v_readlane_b32 s30, v252, 62
	v_readlane_b32 s31, v252, 63
.Lsw0_87:
	s_andn2_saveexec_b64 s[10:11], s[10:11]
	s_cbranch_execz .Lsw0_84
	v_ashrrev_i32_e32 v2, 15, v5
	v_bfe_u32 v7, v5, 6, 2
	v_cmp_eq_u32_e32 vcc, v2, v7
	v_mov_b32_e32 v20, 0
	s_and_saveexec_b64 s[14:15], vcc
	s_cbranch_execz .Lsw0_83
	v_ashrrev_i32_e32 v7, 31, v6
	v_lshlrev_b64 v[6:7], 8, v[6:7]
	v_lshlrev_b64 v[8:9], 6, v[2:3]
	v_lshl_add_u64 v[6:7], v[8:9], 0, v[6:7]
	v_and_or_b32 v6, v5, 63, v6
	v_readlane_b32 s16, v252, 32
	v_lshlrev_b64 v[6:7], 8, v[6:7]
	v_readlane_b32 s28, v252, 44
	v_readlane_b32 s29, v252, 45
	v_lshrrev_b32_e32 v2, 7, v5
	v_and_b32_e32 v2, 0xfc, v2
	v_lshl_add_u64 v[6:7], s[28:29], 0, v[6:7]
	v_lshl_add_u64 v[6:7], v[6:7], 0, v[2:3]
	global_load_dword v20, v[6:7], off
	v_readlane_b32 s17, v252, 33
	v_readlane_b32 s18, v252, 34
	v_readlane_b32 s19, v252, 35
	v_readlane_b32 s20, v252, 36
	v_readlane_b32 s21, v252, 37
	v_readlane_b32 s22, v252, 38
	v_readlane_b32 s23, v252, 39
	v_readlane_b32 s24, v252, 40
	v_readlane_b32 s25, v252, 41
	v_readlane_b32 s26, v252, 42
	v_readlane_b32 s27, v252, 43
	v_readlane_b32 s30, v252, 46
	v_readlane_b32 s31, v252, 47

; __device__ __forceinline__ bf16_t f2bf(float v) { return (bf16_t)(cvt_pk_bf16(v, 0.f) & 0xffffu); }
; __device__ __forceinline__ void prep_phase(const Params& p, LAS unsigned char* lds) {
;     ...
;     for (int e = gt; e < 2 * WSM_L; e += NGT) {
;         const int l = e / WSM_L, r = e % WSM_L; float v;
;         if (r < 256 * 512) { const int n = r >> 9, k = r & 255; const int g = n >> 6, d = n & 63, g2 = k >> 6, c = k & 63; v = (g == g2) ? p.w_fourier[(((size_t)l * 4 + g) * 64 + c) * 64 + d] : 0.f; }
;         else { const int r2 = r - 256 * 512, n = r2 >> 8, k = r2 & 255; v = p.w_conv_out[((size_t)l * 256 + k) * 256 + n]; }
;         ((bf16_t*)(ws + WS_WSM))[e] = f2bf(v);
.Lsw0_84:
	s_or_b64 exec, exec, s[10:11]
	v_add_u32_e32 v4, s0, v4
	v_add_u32_e32 v1, s1, v1
	v_mov_b32_e32 v25, v4
	v_mul_hi_i32 v2, v4, s3
	v_lshrrev_b32_e32 v5, 31, v2
	v_ashrrev_i32_e32 v2, 15, v2
	v_add_u32_e32 v6, v2, v5
	v_mul_i32_i24_e32 v2, 0x30000, v6
	v_sub_u32_e32 v5, v4, v2
	v_cmp_lt_i32_e32 vcc, s12, v5
	s_and_saveexec_b64 s[10:11], vcc
	s_xor_b64 s[10:11], exec, s[10:11]
	s_cbranch_execz .Lsw1_87
	v_lshlrev_b32_e32 v2, 8, v2
	v_ashrrev_i32_e32 v7, 31, v6
	v_sub_u32_e32 v2, v1, v2
	v_readlane_b32 s16, v252, 48
	v_and_b32_e32 v2, 0xff00, v2
	v_lshlrev_b64 v[6:7], 18, v[6:7]
	v_readlane_b32 s22, v252, 54
	v_readlane_b32 s23, v252, 55
	v_add_u32_e32 v5, 0xfffe0000, v5
	v_lshlrev_b32_e32 v2, 2, v2
	v_lshl_add_u64 v[6:7], s[22:23], 0, v[6:7]
	v_lshl_add_u64 v[6:7], v[6:7], 0, v[2:3]
	v_lshrrev_b32_e32 v2, 6, v5
	v_and_b32_e32 v2, 0x3fffffc, v2
	v_lshl_add_u64 v[6:7], v[6:7], 0, v[2:3]
	global_load_dword v21, v[6:7], off
	v_readlane_b32 s17, v252, 49
	v_readlane_b32 s18, v252, 50
	v_readlane_b32 s19, v252, 51
	v_readlane_b32 s20, v252, 52
	v_readlane_b32 s21, v252, 53
	v_readlane_b32 s24, v252, 56
	v_readlane_b32 s25, v252, 57
	v_readlane_b32 s26, v252, 58
	v_readlane_b32 s27, v252, 59
	v_readlane_b32 s28, v252, 60
	v_readlane_b32 s29, v252, 61
	v_readlane_b32 s30, v252, 62
	v_readlane_b32 s31, v252, 63
.Lsw1_87:
	s_andn2_saveexec_b64 s[10:11], s[10:11]
	s_cbranch_execz .Lsw1_84
	v_ashrrev_i32_e32 v2, 15, v5
	v_bfe_u32 v7, v5, 6, 2
	v_cmp_eq_u32_e32 vcc, v2, v7
	v_mov_b32_e32 v21, 0
	s_and_saveexec_b64 s[14:15], vcc
	s_cbranch_execz .Lsw1_83
	v_ashrrev_i32_e32 v7, 31, v6
	v_lshlrev_b64 v[6:7], 8, v[6:7]
	v_lshlrev_b64 v[8:9], 6, v[2:3]
	v_lshl_add_u64 v[6:7], v[8:9], 0, v[6:7]
	v_and_or_b32 v6, v5, 63, v6
	v_readlane_b32 s16, v252, 32
	v_lshlrev_b64 v[6:7], 8, v[6:7]
	v_readlane_b32 s28, v252, 44
	v_readlane_b32 s29, v252, 45
	v_lshrrev_b32_e32 v2, 7, v5
	v_and_b32_e32 v2, 0xfc, v2
	v_lshl_add_u64 v[6:7], s[28:29], 0, v[6:7]
	v_lshl_add_u64 v[6:7], v[6:7], 0, v[2:3]
	global_load_dword v21, v[6:7], off
	v_readlane_b32 s17, v252, 33
	v_readlane_b32 s18, v252, 34
	v_readlane_b32 s19, v252, 35
	v_readlane_b32 s20, v252, 36
	v_readlane_b32 s21, v252, 37
	v_readlane_b32 s22, v252, 38
	v_readlane_b32 s23, v252, 39
	v_readlane_b32 s24, v252, 40
	v_readlane_b32 s25, v252, 41
	v_readlane_b32 s26, v252, 42
	v_readlane_b32 s27, v252, 43
	v_readlane_b32 s30, v252, 46
	v_readlane_b32 s31, v252, 47

; __device__ __forceinline__ bf16_t f2bf(float v) { return (bf16_t)(cvt_pk_bf16(v, 0.f) & 0xffffu); }
; __device__ __forceinline__ void prep_phase(const Params& p, LAS unsigned char* lds) {
;     ...
;     for (int e = gt; e < 2 * WSM_L; e += NGT) {
;         const int l = e / WSM_L, r = e % WSM_L; float v;
;         if (r < 256 * 512) { const int n = r >> 9, k = r & 255; const int g = n >> 6, d = n & 63, g2 = k >> 6, c = k & 63; v = (g == g2) ? p.w_fourier[(((size_t)l * 4 + g) * 64 + c) * 64 + d] : 0.f; }
;         else { const int r2 = r - 256 * 512, n = r2 >> 8, k = r2 & 255; v = p.w_conv_out[((size_t)l * 256 + k) * 256 + n]; }
;         ((bf16_t*)(ws + WS_WSM))[e] = f2bf(v);
.Lsw1_84:
	s_or_b64 exec, exec, s[10:11]
	v_add_u32_e32 v4, s0, v4
	v_add_u32_e32 v1, s1, v1
	v_mov_b32_e32 v26, v4
	v_mul_hi_i32 v2, v4, s3
	v_lshrrev_b32_e32 v5, 31, v2
	v_ashrrev_i32_e32 v2, 15, v2
	v_add_u32_e32 v6, v2, v5
	v_mul_i32_i24_e32 v2, 0x30000, v6
	v_sub_u32_e32 v5, v4, v2
	v_cmp_lt_i32_e32 vcc, s12, v5
	s_and_saveexec_b64 s[10:11], vcc
	s_xor_b64 s[10:11], exec, s[10:11]
	s_cbranch_execz .Lsw2_87
	v_lshlrev_b32_e32 v2, 8, v2
	v_ashrrev_i32_e32 v7, 31, v6
	v_sub_u32_e32 v2, v1, v2
	v_readlane_b32 s16, v252, 48
	v_and_b32_e32 v2, 0xff00, v2
	v_lshlrev_b64 v[6:7], 18, v[6:7]
	v_readlane_b32 s22, v252, 54
	v_readlane_b32 s23, v252, 55
	v_add_u32_e32 v5, 0xfffe0000, v5
	v_lshlrev_b32_e32 v2, 2, v2
	v_lshl_add_u64 v[6:7], s[22:23], 0, v[6:7]
	v_lshl_add_u64 v[6:7], v[6:7], 0, v[2:3]
	v_lshrrev_b32_e32 v2, 6, v5
	v_and_b32_e32 v2, 0x3fffffc, v2
	v_lshl_add_u64 v[6:7], v[6:7], 0, v[2:3]
	global_load_dword v22, v[6:7], off
	v_readlane_b32 s17, v252, 49
	v_readlane_b32 s18, v252, 50
	v_readlane_b32 s19, v252, 51
	v_readlane_b32 s20, v252, 52
	v_readlane_b32 s21, v252, 53
	v_readlane_b32 s24, v252, 56
	v_readlane_b32 s25, v252, 57
	v_readlane_b32 s26, v252, 58
	v_readlane_b32 s27, v252, 59
	v_readlane_b32 s28, v252, 60
	v_readlane_b32 s29, v252, 61
	v_readlane_b32 s30, v252, 62
	v_readlane_b32 s31, v252, 63
.Lsw2_87:
	s_andn2_saveexec_b64 s[10:11], s[10:11]
	s_cbranch_execz .Lsw2_84
	v_ashrrev_i32_e32 v2, 15, v5
	v_bfe_u32 v7, v5, 6, 2
	v_cmp_eq_u32_e32 vcc, v2, v7
	v_mov_b32_e32 v22, 0
	s_and_saveexec_b64 s[14:15], vcc
	s_cbranch_execz .Lsw2_83
	v_ashrrev_i32_e32 v7, 31, v6
	v_lshlrev_b64 v[6:7], 8, v[6:7]
	v_lshlrev_b64 v[8:9], 6, v[2:3]
	v_lshl_add_u64 v[6:7], v[8:9], 0, v[6:7]
	v_and_or_b32 v6, v5, 63, v6
	v_readlane_b32 s16, v252, 32
	v_lshlrev_b64 v[6:7], 8, v[6:7]
	v_readlane_b32 s28, v252, 44
	v_readlane_b32 s29, v252, 45
	v_lshrrev_b32_e32 v2, 7, v5
	v_and_b32_e32 v2, 0xfc, v2
	v_lshl_add_u64 v[6:7], s[28:29], 0, v[6:7]
	v_lshl_add_u64 v[6:7], v[6:7], 0, v[2:3]
	global_load_dword v22, v[6:7], off
	v_readlane_b32 s17, v252, 33
	v_readlane_b32 s18, v252, 34
	v_readlane_b32 s19, v252, 35
	v_readlane_b32 s20, v252, 36
	v_readlane_b32 s21, v252, 37
	v_readlane_b32 s22, v252, 38
	v_readlane_b32 s23, v252, 39
	v_readlane_b32 s24, v252, 40
	v_readlane_b32 s25, v252, 41
	v_readlane_b32 s26, v252, 42
	v_readlane_b32 s27, v252, 43
	v_readlane_b32 s30, v252, 46
	v_readlane_b32 s31, v252, 47

; __device__ __forceinline__ bf16_t f2bf(float v) { return (bf16_t)(cvt_pk_bf16(v, 0.f) & 0xffffu); }
; __device__ __forceinline__ void prep_phase(const Params& p, LAS unsigned char* lds) {
;     ...
;         ((bf16_t*)(ws + WS_WSM))[e] = f2bf(v);
.Lsw2_84:
	s_or_b64 exec, exec, s[10:11]
	v_add_u32_e32 v4, s0, v4
	v_add_u32_e32 v1, s1, v1
	s_waitcnt vmcnt(0)
	v_ashrrev_i32_e32 v5, 31, v24
	v_mov_b32_e32 v4, v24
	v_cvt_pk_bf16_f32 v2, v20, v3
	v_lshl_add_u64 v[6:7], v[4:5], 1, s[6:7]
	global_store_short v[6:7], v2, off
	v_ashrrev_i32_e32 v5, 31, v25
	v_mov_b32_e32 v4, v25
	v_cvt_pk_bf16_f32 v2, v21, v3
	v_lshl_add_u64 v[6:7], v[4:5], 1, s[6:7]
	global_store_short v[6:7], v2, off
	v_ashrrev_i32_e32 v5, 31, v26
	v_mov_b32_e32 v4, v26
	v_cvt_pk_bf16_f32 v2, v22, v3
	v_lshl_add_u64 v[6:7], v[4:5], 1, s[6:7]
	global_store_short v[6:7], v2, off
